# mseq chunk loop fully periodic (unconditional tail loads + chunk-0 stores, padded prologue) with vmcnt 17/15: 4 chunks of prefetch in flight at every step; replaces the earlier mseq wait edit, stacked
# baseline (speedup 1.0000x reference)
; __device__ __forceinline__ unsigned lds_addr(LAS void* p) { return (unsigned)(__UINTPTR_TYPE__)p; }
; __device__ __forceinline__ void mseq_item(Frame& F, int L, int item) {
;     ...
;     const bf16* Km = WSP(bf16, WS_KM); const bf16* Vm = WSP(bf16, WS_VM);
;     const int fr = F.lane & 15, fq = F.lane >> 4, tr_r = (F.lane & 15) >> 2, tr_c = F.lane & 3;
;     const int ktok = F.tid >> 4, kd8 = F.tid & 15, vtok = (F.tid >> 2) & 63, vv8 = F.tid & 3;
;     const bf16* kp = Km + (size_t)(b * SEQ + ktok) * 512 + h * 128 + kd8 * 8; const bf16* vp = Vm + (size_t)(b * SEQ + vtok) * 1024 + h * 256 + 32 * vs + vv8 * 8;
;     const size_t kcs = (size_t)64 * 512, vcs = (size_t)64 * 1024;
;     u32x4 rkA0 = *(const u32x4*)kp, rkA1 = *(const u32x4*)(kp + 32 * 512), rvA = *(const u32x4*)vp;
;     u32x4 rkB0 = *(const u32x4*)(kp + kcs), rkB1 = *(const u32x4*)(kp + kcs + 32 * 512), rvB = *(const u32x4*)(vp + vcs);
;     u32x4 rkC0 = *(const u32x4*)(kp + 2 * kcs), rkC1 = *(const u32x4*)(kp + 2 * kcs + 32 * 512), rvC = *(const u32x4*)(vp + 2 * vcs);
;     u32x4 rkD0 = *(const u32x4*)(kp + 3 * kcs), rkD1 = *(const u32x4*)(kp + 3 * kcs + 32 * 512), rvD = *(const u32x4*)(vp + 3 * vcs);
;     f32x4 acc[2] = {(f32x4){0.f, 0.f, 0.f, 0.f}, (f32x4){0.f, 0.f, 0.f, 0.f}}, nacc = (f32x4){0.f, 0.f, 0.f, 0.f};
;     const u32x4 onesw = (u32x4){0x3f803f80u, 0x3f803f80u, 0x3f803f80u, 0x3f803f80u}; const bf16x8 ones = __builtin_bit_cast(bf16x8, onesw);
;     bf16* Cc = WSP(bf16, WS_CC); float* NCp = WSP(float, WS_NC);
;     const unsigned ldsb = lds_addr(F.lds);
.LBB0_643:
	s_or_b64 exec, exec, s[14:15]
	v_add_u32_e32 v4, s76, v115
	v_ashrrev_i32_e32 v5, 31, v4
	v_lshlrev_b64 v[4:5], 10, v[4:5]
	v_lshl_add_u64 v[4:5], s[4:5], 0, v[4:5]
	s_lshl_b32 s8, s19, 8
	v_lshl_add_u64 v[4:5], v[4:5], 0, s[8:9]
	v_mov_b32_e32 v83, v2
	v_lshl_add_u64 v[44:45], v[4:5], 0, v[82:83]
	v_or_b32_e32 v4, s76, v116
	s_mov_b32 s13, 0x8000
	v_ashrrev_i32_e32 v5, 31, v4
	v_add_co_u32_e32 v8, vcc, s13, v44
	v_lshlrev_b64 v[4:5], 11, v[4:5]
	s_nop 0
	v_addc_co_u32_e32 v9, vcc, 0, v45, vcc
	s_mov_b32 s13, 0x10000
	v_lshl_add_u64 v[4:5], s[6:7], 0, v[4:5]
	s_lshl_b32 s14, s19, 9
	s_mov_b32 s15, s9
	v_add_co_u32_e32 v12, vcc, s13, v44
	v_lshl_add_u64 v[4:5], v[4:5], 0, s[14:15]
	s_lshl_b32 s14, s77, 6
	v_addc_co_u32_e32 v13, vcc, 0, v45, vcc
	s_mov_b32 s13, 0x18000
	v_lshl_add_u64 v[4:5], v[4:5], 0, s[14:15]
	v_mov_b32_e32 v85, v2
	v_add_co_u32_e32 v20, vcc, s13, v44
	v_lshl_add_u64 v[46:47], v[4:5], 0, v[84:85]
	s_nop 0
	v_addc_co_u32_e32 v21, vcc, 0, v45, vcc
	s_mov_b32 s13, 0x20000
	v_add_co_u32_e32 v24, vcc, s13, v46
	s_waitcnt lgkmcnt(0)
	s_nop 0
	v_addc_co_u32_e32 v25, vcc, 0, v47, vcc
	s_barrier
	global_load_dwordx4 v[4:7], v[44:45], off
	global_load_dwordx4 v[16:19], v[46:47], off
	s_nop 0
	global_load_dwordx4 v[8:11], v[8:9], off
	global_load_dword v208, v[44:45], off
	global_load_dword v209, v[44:45], off
	s_nop 0
	global_load_dwordx4 v[12:15], v[12:13], off
	s_nop 0
	global_load_dwordx4 v[20:23], v[20:21], off
	s_nop 0
	global_load_dwordx4 v[28:31], v[24:25], off
	global_load_dword v208, v[44:45], off
	global_load_dword v209, v[44:45], off
	v_add_co_u32_e32 v24, vcc, s13, v44
	s_mov_b32 s13, 0x28000
	s_nop 0
	v_addc_co_u32_e32 v25, vcc, 0, v45, vcc
	v_add_co_u32_e32 v32, vcc, s13, v44
	s_mov_b32 s13, 0x40000
	s_nop 0
	v_addc_co_u32_e32 v33, vcc, 0, v45, vcc
	v_add_co_u32_e32 v36, vcc, s13, v46
	s_mov_b32 s13, 0x30000
	s_nop 0
	v_addc_co_u32_e32 v37, vcc, 0, v47, vcc
	v_add_co_u32_e32 v38, vcc, s13, v44
	s_mov_b32 s13, 0x38000
	s_nop 0
	v_addc_co_u32_e32 v39, vcc, 0, v45, vcc
	v_add_co_u32_e32 v44, vcc, s13, v44
	s_mov_b32 s13, 0x60000
	s_nop 0
	v_addc_co_u32_e32 v45, vcc, 0, v45, vcc
	v_add_co_u32_e32 v48, vcc, s13, v46
	global_load_dwordx4 v[24:27], v[24:25], off
	s_nop 0
	global_load_dwordx4 v[32:35], v[32:33], off
	v_addc_co_u32_e32 v49, vcc, 0, v47, vcc
	global_load_dwordx4 v[40:43], v[36:37], off
	global_load_dword v208, v[44:45], off
	global_load_dword v209, v[44:45], off
	s_nop 0
	global_load_dwordx4 v[36:39], v[38:39], off
	s_nop 0
	global_load_dwordx4 v[44:47], v[44:45], off
	s_nop 0
	global_load_dwordx4 v[48:51], v[48:49], off
	s_and_b32 s13, s73, 0xfffff800
	v_add_u32_e32 v52, s13, v115
	v_ashrrev_i32_e32 v53, 31, v52
	v_lshlrev_b64 v[86:87], 10, v[52:53]
	v_or_b32_e32 v52, s13, v116
	s_and_b32 s17, s74, 7
	v_ashrrev_i32_e32 v53, 31, v52
	s_lshl_b32 s13, s17, 12
	s_lshl_b32 s76, s77, 5
	s_lshl_b32 s16, s12, 5
	v_lshlrev_b64 v[88:89], 11, v[52:53]
	s_cmp_eq_u32 s77, 0
	v_or_b32_e32 v56, v74, v86
	s_cselect_b64 s[14:15], -1, 0
	v_or_b32_e32 v86, s8, v56
	v_or_b32_e32 v56, v76, v88
	s_and_b32 s8, s18, 0x600
	v_or_b32_e32 v56, s8, v56
	v_lshl_or_b32 v88, s17, 6, v56
	s_ashr_i32 s17, s16, 31
	v_or_b32_e32 v52, s13, v122
	s_lshl_b64 s[18:19], s[16:17], 16
	v_lshlrev_b32_e32 v52, 1, v52
	v_mov_b32_e32 v53, v2
	v_or_b32_e32 v54, s13, v123
	v_lshl_add_u64 v[56:57], v[78:79], 0, s[18:19]
	v_lshlrev_b32_e32 v54, 1, v54
	v_mov_b32_e32 v55, v2
	v_lshl_add_u64 v[90:91], v[56:57], 0, v[52:53]
	s_lshl_b64 s[16:17], s[16:17], 9
	v_mov_b32_e32 v52, 0
	s_mov_b32 s13, 0
	s_and_b64 s[14:15], s[14:15], s[68:69]
	v_lshl_add_u64 v[92:93], v[56:57], 0, v[54:55]
	v_lshl_add_u64 v[94:95], v[80:81], 0, s[16:17]
	v_mov_b32_e32 v83, v124
	v_readlane_b32 s8, v254, 6
	v_mov_b32_e32 v53, v52
	v_mov_b32_e32 v54, v52
	v_mov_b32_e32 v55, v52
	v_mov_b32_e32 v56, v52
	v_mov_b32_e32 v57, v52
	v_mov_b32_e32 v58, v52
	v_mov_b32_e32 v59, v52
	v_mov_b32_e32 v60, v52
	v_mov_b32_e32 v61, v52
	v_mov_b32_e32 v62, v52
	v_mov_b32_e32 v63, v52
	v_mov_b32_e32 v105, v52
	v_mov_b32_e32 v106, v52
	v_mov_b32_e32 v107, v52
	v_mov_b32_e32 v108, v52
	v_mov_b32_e32 v85, v52
	v_mov_b32_e32 v96, v52
	v_mov_b32_e32 v97, v52
	v_mov_b32_e32 v104, v52
	s_branch .LBB0_645

.LBB0_645:
	ds_read2_b32 v[98:99], v83 offset1:32
	s_waitcnt vmcnt(17)
	v_and_b32_e32 v131, 0xffff0000, v4
	v_lshlrev_b32_e32 v109, 16, v4
	v_lshlrev_b32_e32 v133, 16, v5
	s_waitcnt lgkmcnt(0)
	v_mul_f32_e32 v131, v98, v131
	v_mul_f32_e32 v109, v98, v109
	v_cvt_pk_bf16_f32 v132, v109, v131
	v_and_b32_e32 v131, 0xffff0000, v5
	v_mul_f32_e32 v109, v98, v133
	v_mul_f32_e32 v131, v98, v131
	v_cvt_pk_bf16_f32 v133, v109, v131
	v_lshlrev_b32_e32 v109, 16, v6
	v_and_b32_e32 v131, 0xffff0000, v6
	v_mul_f32_e32 v109, v98, v109
	v_mul_f32_e32 v131, v98, v131
	v_cvt_pk_bf16_f32 v134, v109, v131
	v_lshlrev_b32_e32 v109, 16, v7
	v_and_b32_e32 v131, 0xffff0000, v7
	v_mul_f32_e32 v109, v98, v109
	v_mul_f32_e32 v98, v98, v131
	v_cvt_pk_bf16_f32 v135, v109, v98
	s_waitcnt vmcnt(15)
	v_lshlrev_b32_e32 v98, 16, v8
	v_and_b32_e32 v109, 0xffff0000, v8
	v_mul_f32_e32 v98, v99, v98
	v_mul_f32_e32 v109, v99, v109
	v_cvt_pk_bf16_f32 v136, v98, v109
	v_lshlrev_b32_e32 v98, 16, v9
	v_and_b32_e32 v109, 0xffff0000, v9
	v_mul_f32_e32 v98, v99, v98
	v_mul_f32_e32 v109, v99, v109
	v_cvt_pk_bf16_f32 v137, v98, v109
	v_lshlrev_b32_e32 v98, 16, v10
	v_and_b32_e32 v109, 0xffff0000, v10
	v_mul_f32_e32 v98, v99, v98
	v_mul_f32_e32 v109, v99, v109
	v_cvt_pk_bf16_f32 v138, v98, v109
	v_lshlrev_b32_e32 v98, 16, v11
	v_and_b32_e32 v109, 0xffff0000, v11
	v_mul_f32_e32 v98, v99, v98
	v_mul_f32_e32 v99, v99, v109
	v_cvt_pk_bf16_f32 v139, v98, v99
	ds_write_b128 v118, v[132:135]
	ds_write_b128 v118, v[136:139] offset:8704
	s_and_saveexec_b64 s[16:17], s[70:71]
	s_cbranch_execz .LBB0_647
	s_waitcnt vmcnt(15)
	ds_write_b128 v119, v[16:19] offset:34816
.LBB0_647:
	s_or_b64 exec, exec, s[16:17]
	s_cmp_eq_u32 s13, 0
	v_lshl_add_u64 v[98:99], s[82:83], 0, v[90:91]
	s_nop 0
	v_cvt_pk_bf16_f32 v106, v105, v106
	v_cvt_pk_bf16_f32 v107, v107, v108
	v_add_co_u32_e32 v108, vcc, 0x3bec4000, v98
	s_nop 1
	v_addc_co_u32_e32 v109, vcc, 0, v99, vcc
	global_store_dwordx2 v[108:109], v[106:107], off
	v_cvt_pk_bf16_f32 v96, v85, v96
	v_cvt_pk_bf16_f32 v97, v97, v104
	v_add_co_u32_e32 v104, vcc, 0x3bec5000, v98
	s_nop 1
	v_addc_co_u32_e32 v105, vcc, 0, v99, vcc
	global_store_dwordx2 v[104:105], v[96:97], off
	s_and_saveexec_b64 s[16:17], s[14:15]
	s_cbranch_execz .LBB0_650
	v_lshl_add_u64 v[96:97], s[82:83], 0, v[94:95]
	global_store_dwordx4 v[96:97], v[52:55], off offset:-1024

.LBB0_651:
	s_cmp_gt_u32 s13, 27
	s_cselect_b64 s[16:17], -1, 0
	s_and_b64 vcc, exec, s[16:17]
	v_lshl_add_u64 v[104:105], s[82:83], 0, v[86:87]
	v_lshl_add_u64 v[96:97], s[82:83], 0, v[88:89]
	s_waitcnt lgkmcnt(0)
	s_barrier
	s_nop 0
	v_add_co_u32_e32 v4, vcc, 0xea40000, v104
	s_nop 1
	v_addc_co_u32_e32 v5, vcc, 0, v105, vcc
	v_add_co_u32_e32 v8, vcc, 0xea48000, v104
	s_nop 1
	v_addc_co_u32_e32 v9, vcc, 0, v105, vcc
	s_nop 0
	v_add_co_u32_e32 v16, vcc, 0xfb00000, v96
	global_load_dwordx4 v[4:7], v[4:5], off
	s_nop 0
	global_load_dwordx4 v[8:11], v[8:9], off
	v_addc_co_u32_e32 v17, vcc, 0, v97, vcc
	global_load_dwordx4 v[16:19], v[16:17], off
.LBB0_653:
	v_mov_b32_e32 v85, s8
	ds_read_b32 v106, v85
	v_add_u32_e32 v131, 0, v120
	v_add_u32_e32 v85, 0, v117
	s_mov_b32 s94, s92
	s_mov_b32 s95, s92
	s_waitcnt lgkmcnt(0)
	v_pk_mul_f32 v[58:59], v[58:59], v[106:107] op_sel_hi:[1,0]
	v_pk_mul_f32 v[56:57], v[56:57], v[106:107] op_sel_hi:[1,0]
	v_pk_mul_f32 v[62:63], v[62:63], v[106:107] op_sel_hi:[1,0]
	v_pk_mul_f32 v[60:61], v[60:61], v[106:107] op_sel_hi:[1,0]
	v_pk_mul_f32 v[54:55], v[54:55], v[106:107] op_sel_hi:[1,0]
	v_pk_mul_f32 v[52:53], v[52:53], v[106:107] op_sel_hi:[1,0]
	ds_read_b64_tr_b16 v[106:107], v131
	ds_read_b64_tr_b16 v[108:109], v125
	ds_read_b64_tr_b16 v[134:135], v126 offset:34816
	ds_read_b64_tr_b16 v[138:139], v126 offset:34848
	ds_read_b64_tr_b16 v[132:133], v85 offset:34816
	ds_read_b64_tr_b16 v[136:137], v85 offset:34848
	s_waitcnt lgkmcnt(1)
	v_mfma_f32_16x16x32_bf16 v[56:59], v[106:109], v[132:135], v[56:59]
	s_mov_b32 s93, s92
	v_mov_b64_e32 v[134:135], s[94:95]
	v_mov_b64_e32 v[132:133], s[92:93]
	s_waitcnt lgkmcnt(0)
	v_mfma_f32_16x16x32_bf16 v[60:63], v[106:109], v[136:139], v[60:63]
	v_mfma_f32_16x16x32_bf16 v[106:109], v[106:109], v[132:135], v[52:55]
	ds_read_b64_tr_b16 v[136:137], v127
	ds_read_b64_tr_b16 v[138:139], v128
	s_nop 0
	ds_read_b64_tr_b16 v[54:55], v130 offset:34816
	ds_read_b64_tr_b16 v[142:143], v130 offset:34848
	ds_read_b64_tr_b16 v[52:53], v129 offset:34816
	ds_read_b64_tr_b16 v[140:141], v129 offset:34848
	s_waitcnt lgkmcnt(1)
	v_mfma_f32_16x16x32_bf16 v[52:55], v[136:139], v[52:55], v[56:59]
	v_mfma_f32_16x16x32_bf16 v[56:59], v[136:139], v[132:135], v[106:109]
	ds_read2_b32 v[134:135], v83 offset0:64 offset1:96
	s_waitcnt vmcnt(17)
	v_and_b32_e32 v132, 0xffff0000, v15
	s_waitcnt vmcnt(15)
	v_and_b32_e32 v133, 0xffff0000, v20
	v_lshlrev_b32_e32 v106, 16, v12
	v_and_b32_e32 v107, 0xffff0000, v12
	s_waitcnt lgkmcnt(0)
	v_mul_f32_e32 v106, v134, v106
	v_mul_f32_e32 v107, v134, v107
	v_cvt_pk_bf16_f32 v106, v106, v107
	v_lshlrev_b32_e32 v107, 16, v13
	v_and_b32_e32 v108, 0xffff0000, v13
	v_mul_f32_e32 v107, v134, v107
	v_mul_f32_e32 v108, v134, v108
	v_cvt_pk_bf16_f32 v107, v107, v108
	v_lshlrev_b32_e32 v108, 16, v14
	v_and_b32_e32 v109, 0xffff0000, v14
	v_mul_f32_e32 v108, v134, v108
	v_mul_f32_e32 v109, v134, v109
	v_cvt_pk_bf16_f32 v108, v108, v109
	v_lshlrev_b32_e32 v109, 16, v15
	v_mul_f32_e32 v109, v134, v109
	v_mul_f32_e32 v132, v134, v132
	v_cvt_pk_bf16_f32 v109, v109, v132
	v_lshlrev_b32_e32 v132, 16, v20
	v_mul_f32_e32 v132, v135, v132
	v_mul_f32_e32 v133, v135, v133
	v_cvt_pk_bf16_f32 v132, v132, v133
	v_lshlrev_b32_e32 v133, 16, v21
	v_and_b32_e32 v134, 0xffff0000, v21
	v_mul_f32_e32 v133, v135, v133
	v_mul_f32_e32 v134, v135, v134
	v_mfma_f32_16x16x32_bf16 v[60:63], v[136:139], v[140:143], v[60:63]
	v_cvt_pk_bf16_f32 v133, v133, v134
	v_lshlrev_b32_e32 v134, 16, v22
	v_and_b32_e32 v136, 0xffff0000, v22
	v_mul_f32_e32 v134, v135, v134
	v_mul_f32_e32 v136, v135, v136
	v_cvt_pk_bf16_f32 v134, v134, v136
	v_lshlrev_b32_e32 v136, 16, v23
	v_and_b32_e32 v137, 0xffff0000, v23
	v_mul_f32_e32 v136, v135, v136
	v_mul_f32_e32 v135, v135, v137
	v_cvt_pk_bf16_f32 v135, v136, v135
	ds_write_b128 v118, v[106:109] offset:17408
	ds_write_b128 v118, v[132:135] offset:26112
	s_and_saveexec_b64 s[18:19], s[70:71]
	s_cbranch_execz .LBB0_655
	s_waitcnt vmcnt(15)
	ds_write_b128 v119, v[28:31] offset:39936

.LBB0_657:
	s_or_b64 exec, exec, s[18:19]
	s_cmp_gt_u32 s13, 26
	s_waitcnt lgkmcnt(0)
	s_barrier
	s_nop 0
	v_add_co_u32_e32 v12, vcc, 0xea50000, v104
	s_nop 1
	v_addc_co_u32_e32 v13, vcc, 0, v105, vcc
	v_add_co_u32_e32 v20, vcc, 0xea58000, v104
	s_nop 1
	v_addc_co_u32_e32 v21, vcc, 0, v105, vcc
	s_nop 0
	v_add_co_u32_e32 v28, vcc, 0xfb20000, v96
	global_load_dwordx4 v[12:15], v[12:13], off
	s_nop 0
	global_load_dwordx4 v[20:23], v[20:21], off
	v_addc_co_u32_e32 v29, vcc, 0, v97, vcc
	global_load_dwordx4 v[28:31], v[28:29], off
.LBB0_659:
	v_mov_b32_e32 v132, s8
	ds_read_b32 v132, v132 offset:4
	s_mov_b32 s94, s92
	s_mov_b32 s95, s92
	s_mov_b32 s93, s92
	s_waitcnt lgkmcnt(0)
	v_pk_mul_f32 v[54:55], v[54:55], v[132:133] op_sel_hi:[1,0]
	v_pk_mul_f32 v[52:53], v[52:53], v[132:133] op_sel_hi:[1,0]
	v_pk_mul_f32 v[62:63], v[62:63], v[132:133] op_sel_hi:[1,0]
	v_pk_mul_f32 v[60:61], v[60:61], v[132:133] op_sel_hi:[1,0]
	v_pk_mul_f32 v[58:59], v[58:59], v[132:133] op_sel_hi:[1,0]
	v_pk_mul_f32 v[56:57], v[56:57], v[132:133] op_sel_hi:[1,0]
	ds_read_b64_tr_b16 v[132:133], v131 offset:17408
	ds_read_b64_tr_b16 v[134:135], v125 offset:17408
	ds_read_b64_tr_b16 v[138:139], v126 offset:39936
	ds_read_b64_tr_b16 v[142:143], v126 offset:39968
	ds_read_b64_tr_b16 v[136:137], v85 offset:39936
	ds_read_b64_tr_b16 v[140:141], v85 offset:39968
	s_waitcnt lgkmcnt(1)
	v_mfma_f32_16x16x32_bf16 v[52:55], v[132:135], v[136:139], v[52:55]
	v_mov_b64_e32 v[138:139], s[94:95]
	v_mov_b64_e32 v[136:137], s[92:93]
	s_waitcnt lgkmcnt(0)
	v_mfma_f32_16x16x32_bf16 v[60:63], v[132:135], v[140:143], v[60:63]
	v_mfma_f32_16x16x32_bf16 v[56:59], v[132:135], v[136:139], v[56:59]
	ds_read_b64_tr_b16 v[132:133], v127 offset:17408
	ds_read_b64_tr_b16 v[134:135], v128 offset:17408
	ds_read_b64_tr_b16 v[142:143], v130 offset:39936
	ds_read_b64_tr_b16 v[146:147], v130 offset:39968
	ds_read_b64_tr_b16 v[140:141], v129 offset:39936
	ds_read_b64_tr_b16 v[144:145], v129 offset:39968
	s_waitcnt lgkmcnt(4)
	v_mfma_f32_16x16x32_bf16 v[56:59], v[132:135], v[136:139], v[56:59]
	ds_read2_b32 v[138:139], v83 offset0:128 offset1:160
	s_waitcnt vmcnt(17)
	v_and_b32_e32 v136, 0xffff0000, v27
	s_waitcnt vmcnt(15)
	v_and_b32_e32 v137, 0xffff0000, v32
	s_waitcnt lgkmcnt(2)
	v_mfma_f32_16x16x32_bf16 v[52:55], v[132:135], v[140:143], v[52:55]
	v_and_b32_e32 v140, 0xffff0000, v34
	s_waitcnt lgkmcnt(0)
	v_mul_f32_e32 v136, v138, v136
	v_mul_f32_e32 v137, v139, v137
	v_mfma_f32_16x16x32_bf16 v[60:63], v[132:135], v[144:147], v[60:63]
	v_lshlrev_b32_e32 v132, 16, v24
	v_and_b32_e32 v133, 0xffff0000, v24
	v_mul_f32_e32 v132, v138, v132
	v_mul_f32_e32 v133, v138, v133
	v_cvt_pk_bf16_f32 v132, v132, v133
	v_lshlrev_b32_e32 v133, 16, v25
	v_and_b32_e32 v134, 0xffff0000, v25
	v_mul_f32_e32 v133, v138, v133
	v_mul_f32_e32 v134, v138, v134
	v_cvt_pk_bf16_f32 v133, v133, v134
	v_lshlrev_b32_e32 v134, 16, v26
	v_and_b32_e32 v135, 0xffff0000, v26
	v_mul_f32_e32 v134, v138, v134
	v_mul_f32_e32 v135, v138, v135
	v_cvt_pk_bf16_f32 v134, v134, v135
	v_lshlrev_b32_e32 v135, 16, v27
	v_mul_f32_e32 v135, v138, v135
	v_cvt_pk_bf16_f32 v135, v135, v136
	v_lshlrev_b32_e32 v136, 16, v32
	v_mul_f32_e32 v136, v139, v136
	v_cvt_pk_bf16_f32 v136, v136, v137
	v_lshlrev_b32_e32 v137, 16, v33
	v_and_b32_e32 v138, 0xffff0000, v33
	v_mul_f32_e32 v137, v139, v137
	v_mul_f32_e32 v138, v139, v138
	v_cvt_pk_bf16_f32 v137, v137, v138
	v_lshlrev_b32_e32 v138, 16, v34
	v_mul_f32_e32 v138, v139, v138
	v_mul_f32_e32 v140, v139, v140
	v_cvt_pk_bf16_f32 v138, v138, v140
	v_lshlrev_b32_e32 v140, 16, v35
	v_and_b32_e32 v141, 0xffff0000, v35
	v_mul_f32_e32 v140, v139, v140
	v_mul_f32_e32 v139, v139, v141
	v_cvt_pk_bf16_f32 v139, v140, v139
	ds_write_b128 v118, v[132:135]
	ds_write_b128 v118, v[136:139] offset:8704
	s_and_saveexec_b64 s[18:19], s[70:71]
	s_cbranch_execz .LBB0_661
	s_waitcnt vmcnt(15)
	ds_write_b128 v119, v[40:43] offset:34816

.LBB0_663:
	s_or_b64 exec, exec, s[18:19]
	s_cmp_gt_u32 s13, 25
	s_waitcnt lgkmcnt(0)
	s_barrier
	s_nop 0
	v_add_co_u32_e32 v24, vcc, 0xea60000, v104
	s_nop 1
	v_addc_co_u32_e32 v25, vcc, 0, v105, vcc
	v_add_co_u32_e32 v32, vcc, 0xea68000, v104
	s_nop 1
	v_addc_co_u32_e32 v33, vcc, 0, v105, vcc
	s_nop 0
	v_add_co_u32_e32 v40, vcc, 0xfb40000, v96
	global_load_dwordx4 v[24:27], v[24:25], off
	s_nop 0
	global_load_dwordx4 v[32:35], v[32:33], off
	v_addc_co_u32_e32 v41, vcc, 0, v97, vcc
	global_load_dwordx4 v[40:43], v[40:41], off
.LBB0_665:
	v_mov_b32_e32 v132, s8
	ds_read_b32 v132, v132 offset:8
	s_mov_b32 s94, s92
	s_mov_b32 s95, s92
	s_mov_b32 s93, s92
	s_waitcnt lgkmcnt(0)
	v_pk_mul_f32 v[54:55], v[54:55], v[132:133] op_sel_hi:[1,0]
	v_pk_mul_f32 v[52:53], v[52:53], v[132:133] op_sel_hi:[1,0]
	v_pk_mul_f32 v[62:63], v[62:63], v[132:133] op_sel_hi:[1,0]
	v_pk_mul_f32 v[60:61], v[60:61], v[132:133] op_sel_hi:[1,0]
	v_pk_mul_f32 v[58:59], v[58:59], v[132:133] op_sel_hi:[1,0]
	v_pk_mul_f32 v[56:57], v[56:57], v[132:133] op_sel_hi:[1,0]
	ds_read_b64_tr_b16 v[132:133], v131
	ds_read_b64_tr_b16 v[134:135], v125
	ds_read_b64_tr_b16 v[138:139], v126 offset:34816
	ds_read_b64_tr_b16 v[142:143], v126 offset:34848
	ds_read_b64_tr_b16 v[136:137], v85 offset:34816
	ds_read_b64_tr_b16 v[140:141], v85 offset:34848
	s_waitcnt lgkmcnt(1)
	v_mfma_f32_16x16x32_bf16 v[52:55], v[132:135], v[136:139], v[52:55]
	v_mov_b64_e32 v[138:139], s[94:95]
	v_mov_b64_e32 v[136:137], s[92:93]
	s_waitcnt lgkmcnt(0)
	v_mfma_f32_16x16x32_bf16 v[60:63], v[132:135], v[140:143], v[60:63]
	v_mfma_f32_16x16x32_bf16 v[56:59], v[132:135], v[136:139], v[56:59]
	ds_read_b64_tr_b16 v[132:133], v127
	ds_read_b64_tr_b16 v[134:135], v128
	ds_read_b64_tr_b16 v[142:143], v130 offset:34816
	ds_read_b64_tr_b16 v[146:147], v130 offset:34848
	ds_read_b64_tr_b16 v[140:141], v129 offset:34816
	ds_read_b64_tr_b16 v[144:145], v129 offset:34848
	s_waitcnt lgkmcnt(4)
	v_mfma_f32_16x16x32_bf16 v[56:59], v[132:135], v[136:139], v[56:59]
	ds_read2_b32 v[138:139], v83 offset0:192 offset1:224
	s_waitcnt vmcnt(17)
	v_and_b32_e32 v136, 0xffff0000, v39
	s_waitcnt vmcnt(15)
	v_and_b32_e32 v137, 0xffff0000, v44
	s_waitcnt lgkmcnt(2)
	v_mfma_f32_16x16x32_bf16 v[52:55], v[132:135], v[140:143], v[52:55]
	v_and_b32_e32 v140, 0xffff0000, v46
	s_waitcnt lgkmcnt(0)
	v_mul_f32_e32 v136, v138, v136
	v_mul_f32_e32 v137, v139, v137
	v_mfma_f32_16x16x32_bf16 v[60:63], v[132:135], v[144:147], v[60:63]
	v_lshlrev_b32_e32 v132, 16, v36
	v_and_b32_e32 v133, 0xffff0000, v36
	v_mul_f32_e32 v132, v138, v132
	v_mul_f32_e32 v133, v138, v133
	v_cvt_pk_bf16_f32 v132, v132, v133
	v_lshlrev_b32_e32 v133, 16, v37
	v_and_b32_e32 v134, 0xffff0000, v37
	v_mul_f32_e32 v133, v138, v133
	v_mul_f32_e32 v134, v138, v134
	v_cvt_pk_bf16_f32 v133, v133, v134
	v_lshlrev_b32_e32 v134, 16, v38
	v_and_b32_e32 v135, 0xffff0000, v38
	v_mul_f32_e32 v134, v138, v134
	v_mul_f32_e32 v135, v138, v135
	v_cvt_pk_bf16_f32 v134, v134, v135
	v_lshlrev_b32_e32 v135, 16, v39
	v_mul_f32_e32 v135, v138, v135
	v_cvt_pk_bf16_f32 v135, v135, v136
	v_lshlrev_b32_e32 v136, 16, v44
	v_mul_f32_e32 v136, v139, v136
	v_cvt_pk_bf16_f32 v136, v136, v137
	v_lshlrev_b32_e32 v137, 16, v45
	v_and_b32_e32 v138, 0xffff0000, v45
	v_mul_f32_e32 v137, v139, v137
	v_mul_f32_e32 v138, v139, v138
	v_cvt_pk_bf16_f32 v137, v137, v138
	v_lshlrev_b32_e32 v138, 16, v46
	v_mul_f32_e32 v138, v139, v138
	v_mul_f32_e32 v140, v139, v140
	v_cvt_pk_bf16_f32 v138, v138, v140
	v_lshlrev_b32_e32 v140, 16, v47
	v_and_b32_e32 v141, 0xffff0000, v47
	v_mul_f32_e32 v140, v139, v140
	v_mul_f32_e32 v139, v139, v141
	v_cvt_pk_bf16_f32 v139, v140, v139
	ds_write_b128 v118, v[132:135] offset:17408
	ds_write_b128 v118, v[136:139] offset:26112
	s_and_saveexec_b64 s[18:19], s[70:71]
	s_cbranch_execz .LBB0_667
	s_waitcnt vmcnt(15)
	ds_write_b128 v119, v[48:51] offset:39936

; __device__ __forceinline__ void mseq_item(Frame& F, int L, int item) {
;     ...
;     float* Cp = F.out + O_CP + ((size_t)L * 32 + bh) * 32768;
; #pragma unroll
;     for (int nt = 0; nt < 2; ++nt)
; #pragma unroll
;         for (int j = 0; j < 4; ++j) Cp[(size_t)(16 * F.wave + 4 * fq + j) * 256 + 32 * vs + 16 * nt + fr] = acc[nt][j];
;     if (vs == 0 && fr == 0) *(f32x4*)(F.out + O_NP + ((size_t)L * 32 + bh) * 128 + 16 * F.wave + 4 * fq) = nacc;
.LBB0_669:
	s_or_b64 exec, exec, s[18:19]
	s_cmp_gt_u32 s13, 24
	s_waitcnt lgkmcnt(0)
	s_barrier
	s_nop 0
	v_add_co_u32_e32 v36, vcc, 0xea70000, v104
	s_nop 1
	v_addc_co_u32_e32 v37, vcc, 0, v105, vcc
	v_add_co_u32_e32 v44, vcc, 0xea78000, v104
	s_nop 1
	v_addc_co_u32_e32 v45, vcc, 0, v105, vcc
	s_nop 0
	v_add_co_u32_e32 v48, vcc, 0xfb60000, v96
	global_load_dwordx4 v[36:39], v[36:37], off
	s_nop 0
	global_load_dwordx4 v[44:47], v[44:45], off
	v_addc_co_u32_e32 v49, vcc, 0, v97, vcc
	global_load_dwordx4 v[48:51], v[48:49], off
	s_branch .LBB0_644
.LBB0_671:
	s_waitcnt vmcnt(0)
	s_ashr_i32 s8, s12, 31
	s_add_u32 s12, s10, s12
	s_addc_u32 s13, s11, s8
	s_lshl_b64 s[16:17], s[12:13], 17
	v_lshl_add_u64 v[4:5], v[0:1], 0, s[16:17]
	s_lshl_b32 s8, s76, 2
	v_lshl_add_u64 v[4:5], v[4:5], 0, s[8:9]
	v_lshl_add_u64 v[6:7], v[4:5], 0, v[64:65]
	v_lshl_add_u64 v[8:9], v[4:5], 0, v[66:67]
	v_lshl_add_u64 v[10:11], v[4:5], 0, v[68:69]
	v_lshl_add_u64 v[4:5], v[4:5], 0, v[70:71]
	global_store_dword v[6:7], v56, off
	global_store_dword v[8:9], v57, off
	global_store_dword v[10:11], v58, off
	global_store_dword v[4:5], v59, off
	global_store_dword v[6:7], v60, off offset:64
	global_store_dword v[8:9], v61, off offset:64
	global_store_dword v[10:11], v62, off offset:64
	global_store_dword v[4:5], v63, off offset:64
	s_and_saveexec_b64 s[16:17], s[14:15]
	s_cbranch_execz .LBB0_625
	s_lshl_b64 s[12:13], s[12:13], 9
	v_lshl_add_u64 v[4:5], v[72:73], 0, s[12:13]
	global_store_dwordx4 v[4:5], v[52:55], off
	s_branch .LBB0_625
